# SSM: negated recurrence coefficients computed once per unit instead of once per block
# baseline (speedup 1.0000x reference)
.LBB0_494:
	s_ashr_i32 s76, s89, 3
	s_lshl_b32 s77, s76, 7
	v_or_b32_e32 v2, s77, v178
	v_ashrrev_i32_e32 v3, 31, v2
	v_or_b32_e32 v6, 32, v2
	v_lshlrev_b64 v[4:5], 5, v[2:3]
	v_ashrrev_i32_e32 v7, 31, v6
	v_or_b32_e32 v8, 64, v2
	v_or_b32_e32 v2, 0x60, v2
	v_lshlrev_b64 v[6:7], 5, v[6:7]
	v_ashrrev_i32_e32 v9, 31, v8
	v_ashrrev_i32_e32 v3, 31, v2
	v_or_b32_e32 v106, s77, v175
	v_lshl_add_u64 v[6:7], v[146:147], 0, v[6:7]
	v_lshlrev_b64 v[8:9], 5, v[8:9]
	v_lshlrev_b64 v[2:3], 5, v[2:3]
	v_ashrrev_i32_e32 v107, 31, v106
	v_or_b32_e32 v108, 64, v106
	v_lshl_add_u64 v[8:9], v[146:147], 0, v[8:9]
	global_load_dwordx4 v[66:69], v[6:7], off
	global_load_dwordx4 v[70:73], v[8:9], off
	v_lshl_add_u64 v[2:3], v[146:147], 0, v[2:3]
	v_lshl_add_u64 v[6:7], v[106:107], 2, s[54:55]
	v_ashrrev_i32_e32 v109, 31, v108
	global_load_dwordx4 v[74:77], v[2:3], off
	s_nop 0
	global_load_dwordx2 v[2:3], v[6:7], off
	v_lshl_add_u64 v[6:7], v[108:109], 2, s[54:55]
	s_lshl_b32 s77, s89, 1
	global_load_dwordx2 v[156:157], v[6:7], off
	v_and_or_b32 v6, s77, 14, v176
	s_lshl_b32 s76, s76, 4
	v_lshl_add_u32 v6, v6, 20, v177
	v_mov_b32_e32 v7, v145
	s_ashr_i32 s77, s76, 31
	v_lshl_add_u64 v[6:7], v[6:7], 0, s[76:77]
	v_lshl_add_u64 v[4:5], v[146:147], 0, v[4:5]
	v_lshl_add_u64 v[98:99], v[6:7], 1, v[148:149]
	global_load_dwordx4 v[78:81], v[4:5], off
	global_load_dwordx4 v[34:37], v[98:99], off
	v_add_co_u32_e32 v4, vcc, s86, v98
	s_lshl_b32 s79, s84, 20
	s_nop 0
	v_addc_co_u32_e32 v5, vcc, 0, v99, vcc
	v_add_co_u32_e32 v6, vcc, 0x8000, v98
	s_and_b32 s79, s79, 0xe00000
	s_nop 0
	v_addc_co_u32_e32 v7, vcc, 0, v99, vcc
	v_add_co_u32_e32 v8, vcc, 0xc000, v98
	v_add_u32_e32 v144, s79, v180
	s_nop 0
	v_addc_co_u32_e32 v9, vcc, 0, v99, vcc
	global_load_dwordx4 v[82:85], v[6:7], off
	global_load_dwordx4 v[90:93], v[8:9], off
	global_load_dwordx4 v[86:89], v[4:5], off
	v_lshl_add_u64 v[4:5], s[76:77], 0, v[144:145]
	v_lshlrev_b64 v[134:135], 1, v[4:5]
	v_lshl_add_u64 v[158:159], v[152:153], 0, v[134:135]
	s_mov_b32 s78, 0
	v_mov_b32_e32 v112, 0
	v_mov_b32_e32 v113, v145
	v_lshl_add_u64 v[100:101], v[98:99], 0, s[70:71]
	v_lshl_add_u64 v[102:103], v[98:99], 0, s[72:73]
	v_lshl_add_u64 v[104:105], v[98:99], 0, s[74:75]
	v_mov_b64_e32 v[110:111], v[158:159]
	v_mov_b32_e32 v114, 0
	v_mov_b32_e32 v115, v145
	s_waitcnt vmcnt(6)
	v_mov_b32_e32 v160, v2
	s_waitcnt vmcnt(5)
	v_mov_b32_e32 v161, v156
	v_mov_b32_e32 v156, v3
	v_xor_b32_e32 v254, 0x80000000, v156
	v_xor_b32_e32 v255, 0x80000000, v157
	s_waitcnt vmcnt(1)
	v_mov_b64_e32 v[96:97], v[92:93]
	v_mov_b64_e32 v[94:95], v[90:91]
	s_branch .LBB0_496
.LBB0_495:
	v_mfma_f32_32x32x16_bf16 v[50:65], v[34:37], v[78:81], 0
	s_add_i32 s78, s78, 1
	v_lshl_add_u64 v[110:111], v[110:111], 0, s[70:71]
	s_cmp_eq_u32 s78, 16
	v_mfma_f32_32x32x16_bf16 v[2:17], v[34:37], v[66:69], 0
	v_mfma_f32_32x32x16_bf16 v[18:33], v[34:37], v[70:73], 0
	v_mfma_f32_32x32x16_bf16 v[34:49], v[34:37], v[74:77], 0
	s_nop 11
	v_fmac_f32_e32 v50, v160, v112
	v_fmac_f32_e32 v2, v161, v113
	v_fmac_f32_e32 v18, v160, v114
	v_fmac_f32_e32 v34, v161, v115
	v_fmac_f32_e32 v50, v254, v114
	v_fmac_f32_e32 v2, v255, v115
	v_fmac_f32_e32 v18, v156, v112
	v_fmac_f32_e32 v34, v157, v113
	v_fmac_f32_e32 v51, v160, v50
	v_fmac_f32_e32 v3, v161, v2
	v_fmac_f32_e32 v19, v160, v18
	v_fmac_f32_e32 v35, v161, v34
	v_fmac_f32_e32 v51, v254, v18
	v_fmac_f32_e32 v3, v255, v34
	v_fmac_f32_e32 v19, v156, v50
	v_fmac_f32_e32 v35, v157, v2
	v_fmac_f32_e32 v52, v160, v51
	v_fmac_f32_e32 v4, v161, v3
	v_fmac_f32_e32 v20, v160, v19
	v_fmac_f32_e32 v36, v161, v35
	v_fmac_f32_e32 v52, v254, v19
	v_fmac_f32_e32 v4, v255, v35
	v_fmac_f32_e32 v20, v156, v51
	v_fmac_f32_e32 v36, v157, v3
	v_fmac_f32_e32 v53, v160, v52
	v_fmac_f32_e32 v5, v161, v4
	v_fmac_f32_e32 v21, v160, v20
	v_fmac_f32_e32 v37, v161, v36
	v_fmac_f32_e32 v53, v254, v20
	v_fmac_f32_e32 v5, v255, v36
	v_fmac_f32_e32 v21, v156, v52
	v_fmac_f32_e32 v37, v157, v4
	v_fmac_f32_e32 v54, v160, v53
	v_fmac_f32_e32 v6, v161, v5
	v_fmac_f32_e32 v22, v160, v21
	v_fmac_f32_e32 v38, v161, v37
	v_fmac_f32_e32 v54, v254, v21
	v_fmac_f32_e32 v6, v255, v37
	v_fmac_f32_e32 v22, v156, v53
	v_fmac_f32_e32 v38, v157, v5
	s_waitcnt vmcnt(1)
	v_mov_b64_e32 v[34:35], v[86:87]
	v_mov_b64_e32 v[36:37], v[88:89]
	v_mov_b64_e32 v[88:89], v[84:85]
	v_mov_b64_e32 v[86:87], v[82:83]
	v_mov_b64_e32 v[82:83], v[90:91]
	v_mov_b64_e32 v[84:85], v[92:93]
	v_fmac_f32_e32 v55, v160, v54
	v_fmac_f32_e32 v7, v161, v6
	v_fmac_f32_e32 v23, v160, v22
	v_fmac_f32_e32 v39, v161, v38
	v_fmac_f32_e32 v55, v254, v22
	v_fmac_f32_e32 v7, v255, v38
	v_fmac_f32_e32 v23, v156, v54
	v_fmac_f32_e32 v39, v157, v6
	v_fmac_f32_e32 v56, v160, v55
	v_fmac_f32_e32 v8, v161, v7
	v_fmac_f32_e32 v24, v160, v23
	v_fmac_f32_e32 v40, v161, v39
	v_fmac_f32_e32 v56, v254, v23
	v_fmac_f32_e32 v8, v255, v39
	v_fmac_f32_e32 v24, v156, v55
	v_fmac_f32_e32 v40, v157, v7
	v_fmac_f32_e32 v57, v160, v56
	v_fmac_f32_e32 v9, v161, v8
	v_fmac_f32_e32 v25, v160, v24
	v_fmac_f32_e32 v41, v161, v40
	v_fmac_f32_e32 v57, v254, v24
	v_fmac_f32_e32 v9, v255, v40
	v_fmac_f32_e32 v25, v156, v56
	v_fmac_f32_e32 v41, v157, v8
	v_fmac_f32_e32 v58, v160, v57
	v_fmac_f32_e32 v10, v161, v9
	v_fmac_f32_e32 v26, v160, v25
	v_fmac_f32_e32 v42, v161, v41
	v_fmac_f32_e32 v58, v254, v25
	v_fmac_f32_e32 v10, v255, v41
	v_fmac_f32_e32 v26, v156, v57
	v_fmac_f32_e32 v42, v157, v9
	v_fmac_f32_e32 v59, v160, v58
	v_fmac_f32_e32 v11, v161, v10
	v_fmac_f32_e32 v27, v160, v26
	v_fmac_f32_e32 v43, v161, v42
	v_fmac_f32_e32 v59, v254, v26
	v_fmac_f32_e32 v11, v255, v42
	v_fmac_f32_e32 v27, v156, v58
	v_fmac_f32_e32 v43, v157, v10
	v_fmac_f32_e32 v60, v160, v59
	v_fmac_f32_e32 v12, v161, v11
	v_fmac_f32_e32 v28, v160, v27
	v_fmac_f32_e32 v44, v161, v43
	v_fmac_f32_e32 v60, v254, v27
	v_fmac_f32_e32 v12, v255, v43
	v_fmac_f32_e32 v28, v156, v59
	v_fmac_f32_e32 v44, v157, v11
	v_fmac_f32_e32 v61, v160, v60
	v_fmac_f32_e32 v13, v161, v12
	v_fmac_f32_e32 v29, v160, v28
	v_fmac_f32_e32 v45, v161, v44
	v_fmac_f32_e32 v61, v254, v28
	v_fmac_f32_e32 v13, v255, v44
	v_fmac_f32_e32 v29, v156, v60
	v_fmac_f32_e32 v45, v157, v12
	v_fmac_f32_e32 v62, v160, v61
	v_fmac_f32_e32 v14, v161, v13
	v_fmac_f32_e32 v30, v160, v29
	v_fmac_f32_e32 v46, v161, v45
	v_fmac_f32_e32 v62, v254, v29
	v_fmac_f32_e32 v14, v255, v45
	v_fmac_f32_e32 v30, v156, v61
	v_fmac_f32_e32 v46, v157, v13
	v_fmac_f32_e32 v63, v160, v62
	v_fmac_f32_e32 v15, v161, v14
	v_fmac_f32_e32 v31, v160, v30
	v_fmac_f32_e32 v47, v161, v46
	v_fmac_f32_e32 v63, v254, v30
	v_fmac_f32_e32 v15, v255, v46
	v_fmac_f32_e32 v31, v156, v62
	v_fmac_f32_e32 v47, v157, v14
	v_fmac_f32_e32 v64, v160, v63
	v_fmac_f32_e32 v16, v161, v15
	v_fmac_f32_e32 v32, v160, v31
	v_fmac_f32_e32 v48, v161, v47
	v_fmac_f32_e32 v64, v254, v31
	v_fmac_f32_e32 v16, v255, v47
	v_fmac_f32_e32 v32, v156, v63
	v_fmac_f32_e32 v48, v157, v15
	v_fmac_f32_e32 v65, v160, v64
	v_fmac_f32_e32 v17, v161, v16
	v_fmac_f32_e32 v33, v160, v32
	v_fmac_f32_e32 v49, v161, v48
	v_fmac_f32_e32 v65, v254, v32
	v_fmac_f32_e32 v17, v255, v48
	v_fmac_f32_e32 v33, v156, v64
	v_fmac_f32_e32 v49, v157, v16
	s_waitcnt vmcnt(0)
	v_mov_b64_e32 v[90:91], v[94:95]
	v_mov_b64_e32 v[92:93], v[96:97]
	v_mov_b32_e32 v112, v65
	v_mov_b32_e32 v113, v17
	v_mov_b32_e32 v114, v33
	v_mov_b32_e32 v115, v49
	s_cbranch_scc1 .LBB0_498

.LBB0_509:
	v_mfma_f32_32x32x16_bf16 v[50:65], v[138:141], v[78:81], 0
	s_add_i32 s76, s76, 1
	v_lshl_add_u64 v[158:159], v[158:159], 0, s[70:71]
	s_cmp_eq_u32 s76, 16
	v_mfma_f32_32x32x16_bf16 v[2:17], v[138:141], v[66:69], 0
	v_mfma_f32_32x32x16_bf16 v[18:33], v[138:141], v[70:73], 0
	v_mfma_f32_32x32x16_bf16 v[34:49], v[138:141], v[74:77], 0
	s_nop 11
	v_fmac_f32_e32 v50, v160, v162
	v_fmac_f32_e32 v2, v161, v163
	v_fmac_f32_e32 v18, v160, v164
	v_fmac_f32_e32 v34, v161, v165
	v_fmac_f32_e32 v50, v254, v164
	v_fmac_f32_e32 v2, v255, v165
	v_fmac_f32_e32 v18, v156, v162
	v_fmac_f32_e32 v34, v157, v163
	v_fmac_f32_e32 v51, v160, v50
	v_fmac_f32_e32 v3, v161, v2
	v_fmac_f32_e32 v19, v160, v18
	v_fmac_f32_e32 v35, v161, v34
	v_fmac_f32_e32 v51, v254, v18
	v_fmac_f32_e32 v3, v255, v34
	v_fmac_f32_e32 v19, v156, v50
	v_fmac_f32_e32 v35, v157, v2
	v_fmac_f32_e32 v52, v160, v51
	v_fmac_f32_e32 v4, v161, v3
	v_fmac_f32_e32 v20, v160, v19
	v_fmac_f32_e32 v36, v161, v35
	v_fmac_f32_e32 v52, v254, v19
	v_fmac_f32_e32 v4, v255, v35
	v_fmac_f32_e32 v20, v156, v51
	v_fmac_f32_e32 v36, v157, v3
	v_fmac_f32_e32 v53, v160, v52
	v_fmac_f32_e32 v5, v161, v4
	v_fmac_f32_e32 v21, v160, v20
	v_fmac_f32_e32 v37, v161, v36
	v_fmac_f32_e32 v53, v254, v20
	v_fmac_f32_e32 v5, v255, v36
	v_fmac_f32_e32 v21, v156, v52
	v_fmac_f32_e32 v37, v157, v4
	v_fmac_f32_e32 v54, v160, v53
	v_fmac_f32_e32 v6, v161, v5
	v_fmac_f32_e32 v22, v160, v21
	v_fmac_f32_e32 v38, v161, v37
	v_fmac_f32_e32 v54, v254, v21
	v_fmac_f32_e32 v6, v255, v37
	v_fmac_f32_e32 v22, v156, v53
	v_fmac_f32_e32 v38, v157, v5
	v_fmac_f32_e32 v55, v160, v54
	v_fmac_f32_e32 v7, v161, v6
	v_fmac_f32_e32 v23, v160, v22
	v_fmac_f32_e32 v39, v161, v38
	v_fmac_f32_e32 v55, v254, v22
	v_fmac_f32_e32 v7, v255, v38
	v_fmac_f32_e32 v23, v156, v54
	v_fmac_f32_e32 v39, v157, v6
	v_fmac_f32_e32 v56, v160, v55
	v_fmac_f32_e32 v8, v161, v7
	v_fmac_f32_e32 v24, v160, v23
	v_fmac_f32_e32 v40, v161, v39
	v_fmac_f32_e32 v56, v254, v23
	v_fmac_f32_e32 v8, v255, v39
	v_fmac_f32_e32 v24, v156, v55
	v_fmac_f32_e32 v40, v157, v7
	v_fmac_f32_e32 v57, v160, v56
	v_fmac_f32_e32 v9, v161, v8
	v_fmac_f32_e32 v25, v160, v24
	v_fmac_f32_e32 v41, v161, v40
	v_fmac_f32_e32 v57, v254, v24
	v_fmac_f32_e32 v9, v255, v40
	v_fmac_f32_e32 v25, v156, v56
	v_fmac_f32_e32 v41, v157, v8
	v_fmac_f32_e32 v58, v160, v57
	v_fmac_f32_e32 v10, v161, v9
	v_fmac_f32_e32 v26, v160, v25
	v_fmac_f32_e32 v42, v161, v41
	v_fmac_f32_e32 v58, v254, v25
	v_fmac_f32_e32 v10, v255, v41
	v_fmac_f32_e32 v26, v156, v57
	v_fmac_f32_e32 v42, v157, v9
	v_fmac_f32_e32 v59, v160, v58
	v_fmac_f32_e32 v11, v161, v10
	v_fmac_f32_e32 v27, v160, v26
	v_fmac_f32_e32 v43, v161, v42
	v_fmac_f32_e32 v59, v254, v26
	v_fmac_f32_e32 v11, v255, v42
	v_fmac_f32_e32 v27, v156, v58
	v_fmac_f32_e32 v43, v157, v10
	v_fmac_f32_e32 v60, v160, v59
	v_fmac_f32_e32 v12, v161, v11
	v_fmac_f32_e32 v28, v160, v27
	v_fmac_f32_e32 v44, v161, v43
	v_fmac_f32_e32 v60, v254, v27
	v_fmac_f32_e32 v12, v255, v43
	v_fmac_f32_e32 v28, v156, v59
	v_fmac_f32_e32 v44, v157, v11
	v_fmac_f32_e32 v61, v160, v60
	v_fmac_f32_e32 v13, v161, v12
	v_fmac_f32_e32 v29, v160, v28
	v_fmac_f32_e32 v45, v161, v44
	v_fmac_f32_e32 v61, v254, v28
	v_fmac_f32_e32 v13, v255, v44
	v_fmac_f32_e32 v29, v156, v60
	v_fmac_f32_e32 v45, v157, v12
	v_fmac_f32_e32 v62, v160, v61
	v_fmac_f32_e32 v14, v161, v13
	v_fmac_f32_e32 v30, v160, v29
	v_fmac_f32_e32 v46, v161, v45
	v_fmac_f32_e32 v62, v254, v29
	v_fmac_f32_e32 v14, v255, v45
	v_fmac_f32_e32 v30, v156, v61
	v_fmac_f32_e32 v46, v157, v13
	v_fmac_f32_e32 v63, v160, v62
	v_fmac_f32_e32 v15, v161, v14
	v_fmac_f32_e32 v31, v160, v30
	v_fmac_f32_e32 v47, v161, v46
	v_fmac_f32_e32 v63, v254, v30
	v_fmac_f32_e32 v15, v255, v46
	v_fmac_f32_e32 v31, v156, v62
	v_fmac_f32_e32 v47, v157, v14
	v_fmac_f32_e32 v64, v160, v63
	v_fmac_f32_e32 v16, v161, v15
	v_fmac_f32_e32 v32, v160, v31
	v_fmac_f32_e32 v48, v161, v47
	v_fmac_f32_e32 v64, v254, v31
	v_fmac_f32_e32 v16, v255, v47
	v_fmac_f32_e32 v32, v156, v63
	v_fmac_f32_e32 v48, v157, v15
	v_fmac_f32_e32 v65, v160, v64
	v_fmac_f32_e32 v17, v161, v16
	v_fmac_f32_e32 v33, v160, v32
	v_fmac_f32_e32 v49, v161, v48
	v_fmac_f32_e32 v65, v254, v32
	v_fmac_f32_e32 v17, v255, v48
	v_fmac_f32_e32 v33, v156, v64
	v_fmac_f32_e32 v49, v157, v16
	v_mov_b32_e32 v162, v65
	v_mov_b32_e32 v163, v17
	v_mov_b32_e32 v164, v33
	v_mov_b32_e32 v165, v49
	v_cvt_pk_bf16_f32 v250, v2, v3
	v_cvt_pk_bf16_f32 v251, v4, v5
	ds_write_b64 v185, v[250:251] offset:2304
	v_cvt_pk_bf16_f32 v252, v6, v7
	v_cvt_pk_bf16_f32 v253, v8, v9
	ds_write_b64 v185, v[252:253] offset:2320
	v_cvt_pk_bf16_f32 v250, v10, v11
	v_cvt_pk_bf16_f32 v251, v12, v13
	ds_write_b64 v185, v[250:251] offset:2336
	v_cvt_pk_bf16_f32 v252, v14, v15
	v_cvt_pk_bf16_f32 v253, v16, v17
	ds_write_b64 v185, v[252:253] offset:2352
	v_mfma_f32_32x32x16_bf16 v[2:17], v[94:97], v[138:141], 0
	v_cvt_pk_bf16_f32 v250, v50, v51
	v_cvt_pk_bf16_f32 v251, v52, v53
	ds_write_b64 v185, v[250:251]
	v_cvt_pk_bf16_f32 v252, v54, v55
	v_cvt_pk_bf16_f32 v253, v56, v57
	ds_write_b64 v185, v[252:253] offset:16
	v_cvt_pk_bf16_f32 v250, v58, v59
	v_cvt_pk_bf16_f32 v251, v60, v61
	ds_write_b64 v185, v[250:251] offset:32
	v_cvt_pk_bf16_f32 v252, v62, v63
	v_cvt_pk_bf16_f32 v253, v64, v65
	ds_write_b64 v185, v[252:253] offset:48
	v_mfma_f32_32x32x16_bf16 v[2:17], v[98:101], v[138:141], v[2:17]
	v_cvt_pk_bf16_f32 v250, v18, v19
	v_cvt_pk_bf16_f32 v251, v20, v21
	ds_write_b64 v185, v[250:251] offset:4608
	v_cvt_pk_bf16_f32 v252, v22, v23
	v_cvt_pk_bf16_f32 v253, v24, v25
	ds_write_b64 v185, v[252:253] offset:4624
	v_cvt_pk_bf16_f32 v250, v26, v27
	v_cvt_pk_bf16_f32 v251, v28, v29
	ds_write_b64 v185, v[250:251] offset:4640
	v_cvt_pk_bf16_f32 v252, v30, v31
	v_cvt_pk_bf16_f32 v253, v32, v33
	ds_write_b64 v185, v[252:253] offset:4656
	v_cvt_pk_bf16_f32 v250, v34, v35
	v_cvt_pk_bf16_f32 v251, v36, v37
	ds_write_b64 v185, v[250:251] offset:6912
	v_cvt_pk_bf16_f32 v252, v38, v39
	v_cvt_pk_bf16_f32 v253, v40, v41
	ds_write_b64 v185, v[252:253] offset:6928
	v_cvt_pk_bf16_f32 v250, v42, v43
	v_cvt_pk_bf16_f32 v251, v44, v45
	ds_write_b64 v185, v[250:251] offset:6944
	v_cvt_pk_bf16_f32 v252, v46, v47
	v_cvt_pk_bf16_f32 v253, v48, v49
	ds_write_b64 v185, v[252:253] offset:6960
	s_waitcnt lgkmcnt(0)
	ds_read_b64_tr_b16 v[18:19], v186
	ds_read_b64_tr_b16 v[20:21], v186 offset:288
	ds_read_b64_tr_b16 v[22:23], v186 offset:1152
	ds_read_b64_tr_b16 v[24:25], v186 offset:1440
	v_mov_b64_e32 v[140:141], v[136:137]
	v_mov_b64_e32 v[138:139], v[134:135]
	s_waitcnt lgkmcnt(2)
	v_mfma_f32_32x32x16_bf16 v[2:17], v[102:105], v[18:21], v[2:17]
	s_waitcnt lgkmcnt(0)
	v_mfma_f32_32x32x16_bf16 v[2:17], v[106:109], v[22:25], v[2:17]
	ds_read_b64_tr_b16 v[18:19], v186 offset:2304
	ds_read_b64_tr_b16 v[20:21], v186 offset:2592
	ds_read_b64_tr_b16 v[22:23], v186 offset:3456
	ds_read_b64_tr_b16 v[24:25], v186 offset:3744
	s_waitcnt lgkmcnt(2)
	v_mfma_f32_32x32x16_bf16 v[2:17], v[110:113], v[18:21], v[2:17]
	s_waitcnt lgkmcnt(0)
	v_mfma_f32_32x32x16_bf16 v[2:17], v[114:117], v[22:25], v[2:17]
	ds_read_b64_tr_b16 v[18:19], v186 offset:4608
	ds_read_b64_tr_b16 v[20:21], v186 offset:4896
	ds_read_b64_tr_b16 v[22:23], v186 offset:5760
	ds_read_b64_tr_b16 v[24:25], v186 offset:6048
	s_waitcnt lgkmcnt(2)
	v_mfma_f32_32x32x16_bf16 v[2:17], v[118:121], v[18:21], v[2:17]
	s_waitcnt lgkmcnt(0)
	v_mfma_f32_32x32x16_bf16 v[2:17], v[122:125], v[22:25], v[2:17]
	ds_read_b64_tr_b16 v[18:19], v186 offset:6912
	ds_read_b64_tr_b16 v[20:21], v186 offset:7200
	ds_read_b64_tr_b16 v[22:23], v186 offset:8064
	ds_read_b64_tr_b16 v[24:25], v186 offset:8352
	s_waitcnt lgkmcnt(0)
	s_waitcnt lgkmcnt(2)
	v_mfma_f32_32x32x16_bf16 v[2:17], v[126:129], v[18:21], v[2:17]
	s_waitcnt lgkmcnt(0)
	v_mfma_f32_32x32x16_bf16 v[2:17], v[130:133], v[22:25], v[2:17]
	s_nop 11
	v_mov_b32_e32 v249, 0xbdd2d3e8
	v_mul_f32_e32 v10, v2, v2
	v_mul_f32_e32 v11, v3, v3
	v_mul_f32_e32 v12, v4, v4
	v_mul_f32_e32 v13, v5, v5
	v_mul_f32_e32 v14, v6, v6
	v_mul_f32_e32 v15, v7, v7
	v_mul_f32_e32 v16, v8, v8
	v_mul_f32_e32 v17, v9, v9
	v_fmaak_f32 v10, v249, v10, 0xc0135761
	v_fmaak_f32 v11, v249, v11, 0xc0135761
	v_fmaak_f32 v12, v249, v12, 0xc0135761
	v_fmaak_f32 v13, v249, v13, 0xc0135761
	v_fmaak_f32 v14, v249, v14, 0xc0135761
	v_fmaak_f32 v15, v249, v15, 0xc0135761
	v_fmaak_f32 v16, v249, v16, 0xc0135761
	v_fmaak_f32 v17, v249, v17, 0xc0135761
	v_mul_f32_e32 v10, v2, v10
	v_mul_f32_e32 v11, v3, v11
	v_mul_f32_e32 v12, v4, v12
	v_mul_f32_e32 v13, v5, v13
	v_mul_f32_e32 v14, v6, v14
	v_mul_f32_e32 v15, v7, v15
	v_mul_f32_e32 v16, v8, v16
	v_mul_f32_e32 v17, v9, v17
	v_exp_f32_e32 v10, v10
	v_exp_f32_e32 v11, v11
	v_exp_f32_e32 v12, v12
	v_exp_f32_e32 v13, v13
	v_exp_f32_e32 v14, v14
	v_exp_f32_e32 v15, v15
	v_exp_f32_e32 v16, v16
	v_exp_f32_e32 v17, v17
	v_add_f32_e32 v10, 1.0, v10
	v_add_f32_e32 v11, 1.0, v11
	v_add_f32_e32 v12, 1.0, v12
	v_add_f32_e32 v13, 1.0, v13
	v_add_f32_e32 v14, 1.0, v14
	v_add_f32_e32 v15, 1.0, v15
	v_add_f32_e32 v16, 1.0, v16
	v_add_f32_e32 v17, 1.0, v17
	v_rcp_f32_e32 v10, v10
	v_rcp_f32_e32 v11, v11
	v_rcp_f32_e32 v12, v12
	v_rcp_f32_e32 v13, v13
	v_rcp_f32_e32 v14, v14
	v_rcp_f32_e32 v15, v15
	v_rcp_f32_e32 v16, v16
	v_rcp_f32_e32 v17, v17
	v_mul_f32_e32 v2, v2, v10
	v_mul_f32_e32 v3, v3, v11
	v_mul_f32_e32 v4, v4, v12
	v_mul_f32_e32 v5, v5, v13
	v_mul_f32_e32 v6, v6, v14
	v_mul_f32_e32 v7, v7, v15
	v_mul_f32_e32 v8, v8, v16
	v_mul_f32_e32 v9, v9, v17
	v_cvt_pk_bf16_f32 v2, v2, v3
	v_cvt_pk_bf16_f32 v3, v4, v5
	v_cvt_pk_bf16_f32 v4, v6, v7
	v_cvt_pk_bf16_f32 v5, v8, v9
	global_store_dwordx2 v[168:169], v[2:3], off
	global_store_dwordx2 v[168:169], v[4:5], off offset:16
	v_lshl_add_u64 v[168:169], v[168:169], 0, s[70:71]
	s_cbranch_scc1 .LBB0_493
	s_waitcnt vmcnt(2)
	v_mov_b64_e32 v[136:137], v[84:85]
	v_mov_b64_e32 v[134:135], v[82:83]
	v_mov_b64_e32 v[82:83], v[90:91]
	v_mov_b64_e32 v[84:85], v[92:93]
	v_mov_b64_e32 v[92:93], v[88:89]
	s_cmp_gt_u32 s76, 11
	v_mov_b64_e32 v[90:91], v[86:87]
	s_cbranch_scc1 .LBB0_509
	s_branch .Lssm2_load
